# combine gate GEMV as packed f32 FMAs over transposed sigmoid tile
# baseline (speedup 1.0000x reference)
; __device__ __forceinline__ float bf2f(u16 v) { return __uint_as_float(((unsigned)v) << 16); }
; __device__ __forceinline__ float sigmoidf_(float x) { return 1.f / (1.f + __expf(-x)); }
; __device__ void phase_combine(const P& p, int l, int ntok, float* lds) {
;     ...
;     for (int e = tid; e < 16 * 96; e += NTHR) {
;       int i = e / 96, m = e % 96;
;       sig[e] = sigmoidf_(bf2f(p.projb[(size_t)(r0 + i) * PROJP + O_RG + m]));
;     }
.LBB0_92:
	s_mov_b32 s20, 0x2aaaaaab
	v_mul_hi_i32 v18, v0, s20
	v_lshrrev_b32_e32 v19, 31, v18
	v_ashrrev_i32_e32 v18, 4, v18
	v_add_u32_e32 v20, v18, v19
	s_movk_i32 s20, 0xffa0
	v_mov_b64_e32 v[2:3], s[94:95]
	v_mad_u64_u32 v[18:19], s[22:23], v20, s20, v[0:1]
	v_lshl_add_u32 v244, v18, 4, v20
	v_add_u32_e32 v20, s56, v20
	v_ashrrev_i32_e32 v19, 31, v18
	v_mad_i64_i32 v[2:3], s[22:23], v20, s33, v[2:3]
	v_lshl_add_u64 v[2:3], v[18:19], 1, v[2:3]
	v_add_co_u32_e32 v2, vcc, s75, v2
	s_nop 1
	v_addc_co_u32_e32 v3, vcc, 0, v3, vcc
	global_load_ushort v241, v[2:3], off offset:1216
	v_add_u32_e32 v0, 0x200, v0
	s_mov_b32 s20, 0x2aaaaaab
	v_mul_hi_i32 v18, v0, s20
	v_lshrrev_b32_e32 v19, 31, v18
	v_ashrrev_i32_e32 v18, 4, v18
	v_add_u32_e32 v20, v18, v19
	s_movk_i32 s20, 0xffa0
	v_mov_b64_e32 v[2:3], s[94:95]
	v_mad_u64_u32 v[18:19], s[22:23], v20, s20, v[0:1]
	v_lshl_add_u32 v245, v18, 4, v20
	v_add_u32_e32 v20, s56, v20
	v_ashrrev_i32_e32 v19, 31, v18
	v_mad_i64_i32 v[2:3], s[22:23], v20, s33, v[2:3]
	v_lshl_add_u64 v[2:3], v[18:19], 1, v[2:3]
	v_add_co_u32_e32 v2, vcc, s75, v2
	s_nop 1
	v_addc_co_u32_e32 v3, vcc, 0, v3, vcc
	global_load_ushort v242, v[2:3], off offset:1216
	v_add_u32_e32 v0, 0x200, v0
	s_mov_b32 s20, 0x2aaaaaab
	v_mul_hi_i32 v18, v0, s20
	v_lshrrev_b32_e32 v19, 31, v18
	v_ashrrev_i32_e32 v18, 4, v18
	v_add_u32_e32 v20, v18, v19
	s_movk_i32 s20, 0xffa0
	v_mov_b64_e32 v[2:3], s[94:95]
	v_mad_u64_u32 v[18:19], s[22:23], v20, s20, v[0:1]
	v_lshl_add_u32 v246, v18, 4, v20
	v_add_u32_e32 v20, s56, v20
	v_ashrrev_i32_e32 v19, 31, v18
	v_mad_i64_i32 v[2:3], s[22:23], v20, s33, v[2:3]
	v_lshl_add_u64 v[2:3], v[18:19], 1, v[2:3]
	v_add_co_u32_e32 v2, vcc, s75, v2
	s_nop 1
	v_addc_co_u32_e32 v3, vcc, 0, v3, vcc
	global_load_ushort v243, v[2:3], off offset:1216
	v_add_u32_e32 v0, 0x200, v0
	s_waitcnt vmcnt(0)
	v_lshlrev_b32_e32 v241, 16, v241
	v_mul_f32_e32 v241, 0xbfb8aa3b, v241
	v_exp_f32_e32 v241, v241
	v_lshlrev_b32_e32 v242, 16, v242
	v_mul_f32_e32 v242, 0xbfb8aa3b, v242
	v_exp_f32_e32 v242, v242
	v_lshlrev_b32_e32 v243, 16, v243
	v_mul_f32_e32 v243, 0xbfb8aa3b, v243
	v_exp_f32_e32 v243, v243
	v_add_f32_e32 v241, 1.0, v241
	v_add_f32_e32 v242, 1.0, v242
	v_add_f32_e32 v243, 1.0, v243
	v_rcp_f32_e32 v241, v241
	v_rcp_f32_e32 v242, v242
	v_rcp_f32_e32 v243, v243
	s_nop 0
	v_lshlrev_b32_e32 v244, 2, v244
	ds_write_b32 v244, v241
	v_lshlrev_b32_e32 v245, 2, v245
	ds_write_b32 v245, v242
	v_lshlrev_b32_e32 v246, 2, v246
	ds_write_b32 v246, v243

; __device__ void phase_combine(const P& p, int l, int ntok, float* lds) {
;     ...
;       for (int i = 0; i < 4; ++i) {
;         int row = r0 + i0 + i, t = tb + i0 + i;
;         y0[i] = or0[(size_t)row * 512 + tid]; y1[i] = or1[(size_t)row * 512 + tid];
;         const u16* pv = p.projb + (size_t)row * PROJP + O_RKV + 1024 + tid;
;         vc[i] = pv[0]; vp[i] = pv[t > 0 ? -PROJP : 0]; vn[i] = pv[t < T - 1 ? PROJP : 0];
;         sf[i] = p.sbon[(size_t)row * 8 + wv]; sb[i] = p.sbon[(size_t)NT * 8 + (size_t)row * 8 + wv];
;         size_t ob = (size_t)row * 512 + hh * 128 + lane;
;         a0[i] = om0[ob]; a1[i] = om1[ob]; a2[i] = om0[ob + 64]; a3[i] = om1[ob + 64];
;         const u16* pg = p.projb + (size_t)row * PROJP + gch;
;         g0r[i] = pg[0]; g1r[i] = pg[64];
;         cbr[i] = p.projb[(size_t)row * PROJP + O_CB + tid];
;       }
.LBB0_94:
	s_or_b32 s46, s60, s56
	s_ashr_i32 s47, s46, 31
	s_lshl_b64 s[0:1], s[46:47], 9
	s_or_b32 s2, s60, s59
	v_lshl_add_u64 v[0:1], s[0:1], 0, v[4:5]
	s_mul_i32 s20, s46, 0x3600
	v_lshlrev_b64 v[0:1], 1, v[0:1]
	s_mul_hi_i32 s3, s46, 0x3600
	s_add_u32 s22, s94, s20
	v_lshl_add_u64 v[2:3], s[34:35], 0, v[0:1]
	v_lshl_add_u64 v[0:1], s[62:63], 0, v[0:1]
	s_addc_u32 s23, s95, s3
	v_lshlrev_b64 v[22:23], 1, v[4:5]
	v_sub_co_u32_e64 v139, s[52:53], s2, 1
	global_load_ushort v201, v[2:3], off
	global_load_ushort v202, v[0:1], off
	v_lshl_add_u64 v[0:1], s[22:23], 0, v[22:23]
	s_and_b64 s[24:25], s[52:53], exec
	v_add_co_u32_e32 v18, vcc, s75, v0
	s_cselect_b32 s25, 0, -1
	s_cselect_b32 s24, 0, 0xffffca00
	s_cmp_lt_u32 s2, s57
	v_lshl_add_u64 v[2:3], v[0:1], 0, s[68:69]
	v_addc_co_u32_e32 v19, vcc, 0, v1, vcc
	s_cselect_b64 s[44:45], -1, 0
	global_load_ushort v199, v[18:19], off offset:64
	v_lshl_add_u64 v[18:19], v[2:3], 0, s[24:25]
	s_and_b64 s[24:25], s[44:45], exec
	s_cselect_b32 s28, 0x3600, 0
	v_lshl_add_u64 v[2:3], v[2:3], 0, s[28:29]
	s_lshl_b64 s[24:25], s[46:47], 5
	global_load_ushort v208, v[18:19], off
	global_load_ushort v210, v[2:3], off
	s_add_u32 s24, s10, s24
	v_mov_b32_e32 v19, s1
	v_or_b32_e32 v18, s0, v10
	s_addc_u32 s25, s11, s25
	v_lshlrev_b64 v[18:19], 1, v[18:19]
	s_or_b32 s50, s46, 1
	v_lshl_add_u64 v[20:21], v[6:7], 0, v[18:19]
	v_lshl_add_u64 v[18:19], v[8:9], 0, v[18:19]
	s_ashr_i32 s51, s50, 31
	global_load_ushort v195, v[20:21], off
	global_load_ushort v193, v[18:19], off
	global_load_ushort v196, v[20:21], off offset:128
	global_load_ushort v194, v[18:19], off offset:128
	global_load_ushort v192, v134, s[22:23]
	global_load_ushort v191, v134, s[22:23] offset:128
	v_add_co_u32_e32 v18, vcc, s96, v0
	s_or_b32 s3, s2, 1
	s_lshl_b64 s[0:1], s[50:51], 9
	s_mul_i32 s22, s50, 0x3600
	v_addc_co_u32_e32 v19, vcc, 0, v1, vcc
	s_mul_hi_i32 s20, s50, 0x3600
	s_add_u32 s22, s94, s22
	global_load_ushort v138, v[18:19], off offset:3136
	v_lshl_add_u64 v[18:19], s[0:1], 0, v[4:5]
	s_addc_u32 s23, s95, s20
	v_lshlrev_b64 v[18:19], 1, v[18:19]
	s_cmp_lt_u32 s3, s57
	v_lshl_add_u64 v[20:21], s[34:35], 0, v[18:19]
	v_lshl_add_u64 v[18:19], s[62:63], 0, v[18:19]
	s_cselect_b64 s[42:43], -1, 0
	v_lshl_add_u64 v[2:3], s[24:25], 0, v[16:17]
	global_load_ushort v212, v[20:21], off
	global_load_ushort v213, v[18:19], off
	v_lshl_add_u64 v[20:21], s[22:23], 0, v[22:23]
	s_and_b64 s[24:25], s[42:43], exec
	v_lshl_add_u64 v[18:19], v[20:21], 0, s[68:69]
	v_add_co_u32_e32 v136, vcc, s75, v20
	s_cselect_b32 s28, 0x3600, 0
	s_nop 0
	v_addc_co_u32_e32 v137, vcc, 0, v21, vcc
	v_lshl_add_u64 v[18:19], v[18:19], 0, s[28:29]
	s_lshl_b64 s[24:25], s[50:51], 5
	global_load_ushort v198, v[136:137], off offset:64
	global_load_ushort v206, v[18:19], off
	s_add_u32 s24, s10, s24
	v_mov_b32_e32 v137, s1
	v_or_b32_e32 v136, s0, v10
	s_addc_u32 s25, s11, s25
	v_lshlrev_b64 v[136:137], 1, v[136:137]
	s_or_b32 s48, s46, 2
	v_lshl_add_u64 v[140:141], v[6:7], 0, v[136:137]
	v_lshl_add_u64 v[136:137], v[8:9], 0, v[136:137]
	s_ashr_i32 s49, s48, 31
	global_load_ushort v167, v[140:141], off
	global_load_ushort v165, v[136:137], off
	global_load_ushort v190, v[140:141], off offset:128
	global_load_ushort v166, v[136:137], off offset:128
	global_load_ushort v164, v134, s[22:23]
	global_load_ushort v163, v134, s[22:23] offset:128
	v_add_co_u32_e32 v20, vcc, s96, v20
	s_or_b32 s23, s2, 2
	s_lshl_b64 s[0:1], s[48:49], 9
	s_mul_i32 s22, s48, 0x3600
	v_lshl_add_u64 v[18:19], s[24:25], 0, v[16:17]
	v_addc_co_u32_e32 v21, vcc, 0, v21, vcc
	s_mul_hi_i32 s20, s48, 0x3600
	s_add_u32 s24, s94, s22
	global_load_ushort v137, v[20:21], off offset:3136
	v_lshl_add_u64 v[20:21], s[0:1], 0, v[4:5]
	s_addc_u32 s25, s95, s20
	v_lshlrev_b64 v[20:21], 1, v[20:21]
	s_cmp_lt_u32 s23, s57
	v_lshl_add_u64 v[140:141], s[34:35], 0, v[20:21]
	v_lshl_add_u64 v[20:21], s[62:63], 0, v[20:21]
	s_cselect_b64 s[40:41], -1, 0
	global_load_ushort v209, v[140:141], off
	global_load_ushort v211, v[20:21], off
	v_lshl_add_u64 v[140:141], s[24:25], 0, v[22:23]
	s_and_b64 s[26:27], s[40:41], exec
	v_lshl_add_u64 v[20:21], v[140:141], 0, s[68:69]
	v_add_co_u32_e32 v142, vcc, s75, v140
	s_cselect_b32 s28, 0x3600, 0
	s_lshl_b64 s[26:27], s[48:49], 5
	v_addc_co_u32_e32 v143, vcc, 0, v141, vcc
	v_lshl_add_u64 v[20:21], v[20:21], 0, s[28:29]
	s_add_u32 s26, s10, s26
	global_load_ushort v197, v[142:143], off offset:64
	global_load_ushort v204, v[20:21], off
	s_addc_u32 s27, s11, s27
	v_mov_b32_e32 v143, s1
	v_or_b32_e32 v142, s0, v10
	s_or_b32 s36, s46, 3
	v_lshlrev_b64 v[142:143], 1, v[142:143]
	v_add_co_u32_e32 v140, vcc, s96, v140
	s_ashr_i32 s37, s36, 31
	v_lshl_add_u64 v[144:145], v[6:7], 0, v[142:143]
	v_lshl_add_u64 v[142:143], v[8:9], 0, v[142:143]
	v_addc_co_u32_e32 v141, vcc, 0, v141, vcc
	s_lshl_b64 s[0:1], s[36:37], 9
	v_lshl_add_u64 v[20:21], s[26:27], 0, v[16:17]
	global_load_ushort v161, v[144:145], off
	global_load_ushort v159, v[142:143], off
	global_load_ushort v162, v[144:145], off offset:128
	global_load_ushort v160, v[142:143], off offset:128
	global_load_ushort v158, v134, s[24:25]
	global_load_ushort v157, v134, s[24:25] offset:128
	global_load_ushort v136, v[140:141], off offset:3136
	s_or_b32 s26, s2, 3
	v_lshl_add_u64 v[140:141], s[0:1], 0, v[4:5]
	s_mul_i32 s22, s36, 0x3600
	v_lshlrev_b64 v[140:141], 1, v[140:141]
	s_mul_hi_i32 s20, s36, 0x3600
	s_add_u32 s24, s94, s22
	v_lshl_add_u64 v[142:143], s[34:35], 0, v[140:141]
	v_lshl_add_u64 v[140:141], s[62:63], 0, v[140:141]
	s_addc_u32 s25, s95, s20
	global_load_ushort v205, v[142:143], off
	global_load_ushort v207, v[140:141], off
; #define PIN8(a, o) asm volatile("" : "+v"(a[o]), "+v"(a[o + 1]), "+v"(a[o + 2]), "+v"(a[o + 3]), "+v"(a[o + 4]), "+v"(a[o + 5]), "+v"(a[o + 6]), "+v"(a[o + 7]))
; #define PIN8(a) asm volatile("" : "+v"(a[0]), "+v"(a[1]), "+v"(a[2]), "+v"(a[3]))
; __device__ void phase_combine(const P& p, int l, int ntok, float* lds) {
;     ...
;         const u16* pc = p.projb + (size_t)(r0 + i0) * PROJP;
; #pragma unroll
;         for (int j = 0; j < 6; ++j) {
;           int t = tb + i0 + j - 1;
;           int off = (t < 0 ? 0 : (t > T - 1 ? T - 1 : t)) - (tb + i0);
;           const u16* pr = pc + (long)off * PROJP;
;           ucc[j] = pr[O_CC + tid]; uch[j] = pr[O_CH + tid];
;         }
;       }
;       PIN8(y0); PIN8(y1); PIN8(sf); PIN8(sb); PIN8(a0); PIN8(a1); PIN8(a2); PIN8(a3);
;       PIN8(vc); PIN8(vp); PIN8(vn); PIN8(g0r); PIN8(g1r); PIN8(cbr); PIN8(ucc); PIN8(uch);
;       asm volatile("" : "+v"(ucc[4]), "+v"(ucc[5]), "+v"(uch[4]), "+v"(uch[5]));
;       {
;         float gate[4];
; #pragma unroll
;         for (int i = 0; i < 4; ++i) gate[i] = 0.f;
; #pragma unroll
;         for (int m = 0; m < 96; m += 4) {
; #pragma unroll
;           for (int i = 0; i < 4; ++i) {
;             float4 s = *reinterpret_cast<const float4*>(sig + (i0 + i) * 96 + m);
;             gate[i] += s.x * g2r[m] + s.y * g2r[m + 1] + s.z * g2r[m + 2] + s.w * g2r[m + 3];
	v_lshl_add_u64 v[140:141], s[24:25], 0, v[22:23]
	v_add_co_u32_e32 v142, vcc, s75, v140
	s_cmp_lt_u32 s26, s57
	s_nop 0
	v_addc_co_u32_e32 v143, vcc, 0, v141, vcc
	s_cselect_b64 vcc, -1, 0
	s_and_b64 s[30:31], vcc, exec
	v_lshl_add_u64 v[22:23], v[140:141], 0, s[68:69]
	s_cselect_b32 s28, 0x3600, 0
	v_lshl_add_u64 v[22:23], v[22:23], 0, s[28:29]
	global_load_ushort v200, v[142:143], off offset:64
	global_load_ushort v203, v[22:23], off
	v_mov_b32_e32 v143, s1
	v_or_b32_e32 v142, s0, v10
	v_min_i32_e32 v139, s57, v139
	v_lshlrev_b64 v[142:143], 1, v[142:143]
	v_add_co_u32_e64 v140, s[0:1], s96, v140
	v_cndmask_b32_e64 v139, v139, 0, s[52:53]
	v_lshl_add_u64 v[144:145], v[6:7], 0, v[142:143]
	v_lshl_add_u64 v[142:143], v[8:9], 0, v[142:143]
	v_addc_co_u32_e64 v141, s[0:1], 0, v141, s[0:1]
	v_subrev_u32_e32 v139, s2, v139
	global_load_ushort v155, v[144:145], off
	global_load_ushort v153, v[142:143], off
	global_load_ushort v156, v[144:145], off offset:128
	global_load_ushort v154, v[142:143], off offset:128
	global_load_ushort v152, v134, s[24:25]
	global_load_ushort v149, v134, s[24:25] offset:128
	global_load_ushort v135, v[140:141], off offset:3136
	v_mad_i64_i32 v[140:141], s[0:1], v139, s61, v[0:1]
	v_add_co_u32_e64 v140, s[0:1], s78, v140
	s_lshl_b64 s[30:31], s[36:37], 5
	s_nop 0
	v_addc_co_u32_e64 v141, s[0:1], 0, v141, s[0:1]
	global_load_ushort v139, v[140:141], off offset:64
	s_nop 0
	global_load_ushort v140, v[140:141], off offset:1088
	v_mov_b32_e32 v141, s57
	v_sub_u32_e64 v141, s2, v141 clamp
	v_sub_u32_e32 v141, 0, v141
	v_mad_i64_i32 v[142:143], s[0:1], v141, s61, v[0:1]
	v_add_co_u32_e64 v142, s[0:1], s78, v142
	s_add_u32 s30, s10, s30
	s_nop 0
	v_addc_co_u32_e64 v143, s[0:1], 0, v143, s[0:1]
	s_addc_u32 s31, s11, s31
	s_min_u32 s0, s3, s57
	s_sub_i32 s0, s0, s2
	global_load_ushort v147, v[142:143], off offset:64
	global_load_ushort v148, v[142:143], off offset:1088
	v_mad_i64_i32 v[142:143], s[0:1], s0, v179, v[0:1]
	v_add_co_u32_e64 v142, s[0:1], s78, v142
	v_lshl_add_u64 v[22:23], s[30:31], 0, v[16:17]
	s_nop 0
	v_addc_co_u32_e64 v143, s[0:1], 0, v143, s[0:1]
	s_min_u32 s0, s23, s57
	s_sub_i32 s0, s0, s2
	global_load_ushort v150, v[142:143], off offset:64
	global_load_ushort v151, v[142:143], off offset:1088
	v_mad_i64_i32 v[142:143], s[0:1], s0, v179, v[0:1]
	v_add_co_u32_e64 v142, s[0:1], s78, v142
	s_waitcnt vmcnt(25)
	v_mov_b32_e32 v216, v197
	v_addc_co_u32_e64 v143, s[0:1], 0, v143, s[0:1]
	s_min_u32 s0, s26, s57
	s_sub_i32 s0, s0, s2
	global_load_ushort v145, v[142:143], off offset:64
	global_load_ushort v146, v[142:143], off offset:1088
	v_mad_i64_i32 v[142:143], s[0:1], s0, v179, v[0:1]
	v_add_co_u32_e64 v214, s[0:1], s78, v142
	s_nop 1
	v_addc_co_u32_e64 v215, s[0:1], 0, v143, s[0:1]
	s_add_i32 s0, s2, 4
	s_min_u32 s0, s0, s57
	s_sub_i32 s0, s0, s2
	v_mad_i64_i32 v[0:1], s[0:1], s0, v179, v[0:1]
	v_add_co_u32_e64 v0, s[0:1], s78, v0
	global_load_ushort v143, v[214:215], off offset:64
	global_load_ushort v144, v[214:215], off offset:1088
	v_addc_co_u32_e64 v1, s[0:1], 0, v1, s[0:1]
	global_load_ushort v141, v[0:1], off offset:64
	global_load_ushort v142, v[0:1], off offset:1088
	global_load_dword v218, v[2:3], off
	global_load_dword v214, v[22:23], off
	global_load_dword v215, v[20:21], off
	global_load_dword v217, v[18:19], off
	v_add_co_u32_e64 v0, s[0:1], s66, v2
	s_lshl_b64 s[2:3], s[48:49], 12
	s_nop 0
	v_addc_co_u32_e64 v1, s[0:1], 0, v3, s[0:1]
	global_load_dword v219, v[0:1], off
	v_add_co_u32_e64 v0, s[0:1], s66, v22
	s_nop 1
	v_addc_co_u32_e64 v1, s[0:1], 0, v23, s[0:1]
	global_load_dword v22, v[0:1], off
	v_add_co_u32_e64 v0, s[0:1], s66, v20
	s_nop 1
	v_addc_co_u32_e64 v1, s[0:1], 0, v21, s[0:1]
	global_load_dword v23, v[0:1], off
	v_add_co_u32_e64 v0, s[0:1], s66, v18
	v_mov_b32_e32 v21, v198
	s_nop 0
	v_addc_co_u32_e64 v1, s[0:1], 0, v19, s[0:1]
	s_lshl_b32 s0, s60, 2
	s_add_i32 s0, s0, 0
	global_load_dword v20, v[0:1], off
	v_mov_b32_e32 v18, v199
	v_mov_b32_e32 v19, s0
	s_waitcnt lgkmcnt(0)
	ds_read_b128 v[220:223], v19
	ds_read_b128 v[224:227], v19 offset:64
	ds_read_b128 v[228:231], v19 offset:128
	ds_read_b128 v[244:247], v19 offset:192
	ds_read_b128 v[248:251], v19 offset:256
	ds_read_b128 v[252:255], v19 offset:320
	s_waitcnt lgkmcnt(5)
	v_pk_mul_f32 v[232:233], v[220:221], v[90:91] op_sel_hi:[1,0]
	v_pk_mul_f32 v[234:235], v[222:223], v[90:91] op_sel_hi:[1,0]
	ds_read_b128 v[0:3], v19 offset:384
	s_waitcnt lgkmcnt(5)
	v_pk_mul_f32 v[236:237], v[224:225], v[90:91] op_sel:[0,1]
	v_pk_mul_f32 v[242:243], v[226:227], v[90:91] op_sel:[0,1]
	ds_read_b128 v[220:223], v19 offset:448
	s_waitcnt lgkmcnt(5)
	v_pk_fma_f32 v[232:233], v[228:229], v[32:33], v[232:233] op_sel_hi:[1,0,1]
	v_pk_fma_f32 v[234:235], v[230:231], v[32:33], v[234:235] op_sel_hi:[1,0,1]
	ds_read_b128 v[224:227], v19 offset:512
	s_waitcnt lgkmcnt(5)
	v_pk_fma_f32 v[236:237], v[244:245], v[92:93], v[236:237] op_sel_hi:[1,0,1]
	v_pk_fma_f32 v[242:243], v[246:247], v[92:93], v[242:243] op_sel_hi:[1,0,1]
	ds_read_b128 v[228:231], v19 offset:576
	s_waitcnt lgkmcnt(5)
	v_pk_fma_f32 v[232:233], v[248:249], v[32:33], v[232:233] op_sel:[0,1,0]
	v_pk_fma_f32 v[234:235], v[250:251], v[32:33], v[234:235] op_sel:[0,1,0]
	ds_read_b128 v[244:247], v19 offset:640
	s_waitcnt lgkmcnt(5)
	v_pk_fma_f32 v[236:237], v[252:253], v[78:79], v[236:237] op_sel_hi:[1,0,1]
	v_pk_fma_f32 v[242:243], v[254:255], v[78:79], v[242:243] op_sel_hi:[1,0,1]
	ds_read_b128 v[248:251], v19 offset:704
	s_waitcnt lgkmcnt(5)
	v_pk_fma_f32 v[232:233], v[0:1], v[78:79], v[232:233] op_sel:[0,1,0]
	v_pk_fma_f32 v[234:235], v[2:3], v[78:79], v[234:235] op_sel:[0,1,0]
	ds_read_b128 v[252:255], v19 offset:768
	s_waitcnt lgkmcnt(5)
; __device__ void phase_combine(const P& p, int l, int ntok, float* lds) {
;     ...
; #pragma unroll
;         for (int m = 0; m < 96; m += 4) {
; #pragma unroll
;           for (int i = 0; i < 4; ++i) {
;             float4 s = *reinterpret_cast<const float4*>(sig + (i0 + i) * 96 + m);
;             gate[i] += s.x * g2r[m] + s.y * g2r[m + 1] + s.z * g2r[m + 2] + s.w * g2r[m + 3];
	v_pk_fma_f32 v[236:237], v[220:221], v[92:93], v[236:237] op_sel:[0,1,0]
	v_pk_fma_f32 v[242:243], v[222:223], v[92:93], v[242:243] op_sel:[0,1,0]
	ds_read_b128 v[0:3], v19 offset:832
	s_waitcnt lgkmcnt(5)
	v_pk_fma_f32 v[232:233], v[224:225], v[80:81], v[232:233] op_sel_hi:[1,0,1]
	v_pk_fma_f32 v[234:235], v[226:227], v[80:81], v[234:235] op_sel_hi:[1,0,1]
	ds_read_b128 v[220:223], v19 offset:896
	s_waitcnt lgkmcnt(5)
	v_pk_fma_f32 v[236:237], v[228:229], v[80:81], v[236:237] op_sel:[0,1,0]
	v_pk_fma_f32 v[242:243], v[230:231], v[80:81], v[242:243] op_sel:[0,1,0]
	ds_read_b128 v[224:227], v19 offset:960
	s_waitcnt lgkmcnt(5)
	v_pk_fma_f32 v[232:233], v[244:245], v[82:83], v[232:233] op_sel_hi:[1,0,1]
	v_pk_fma_f32 v[234:235], v[246:247], v[82:83], v[234:235] op_sel_hi:[1,0,1]
	ds_read_b128 v[228:231], v19 offset:1024
	s_waitcnt lgkmcnt(5)
	v_pk_fma_f32 v[236:237], v[248:249], v[10:11], v[236:237] op_sel:[0,1,0]
	v_pk_fma_f32 v[242:243], v[250:251], v[10:11], v[242:243] op_sel:[0,1,0]
	ds_read_b128 v[244:247], v19 offset:1088
	s_waitcnt lgkmcnt(5)
	v_pk_fma_f32 v[232:233], v[252:253], v[82:83], v[232:233] op_sel:[0,1,0]
	v_pk_fma_f32 v[234:235], v[254:255], v[82:83], v[234:235] op_sel:[0,1,0]
	ds_read_b128 v[248:251], v19 offset:1152
	s_waitcnt lgkmcnt(5)
	v_pk_fma_f32 v[236:237], v[0:1], v[84:85], v[236:237] op_sel_hi:[1,0,1]
	v_pk_fma_f32 v[242:243], v[2:3], v[84:85], v[242:243] op_sel_hi:[1,0,1]
	ds_read_b128 v[252:255], v19 offset:1216
	s_waitcnt lgkmcnt(5)
	v_pk_fma_f32 v[232:233], v[220:221], v[84:85], v[232:233] op_sel:[0,1,0]
	v_pk_fma_f32 v[234:235], v[222:223], v[84:85], v[234:235] op_sel:[0,1,0]
	ds_read_b128 v[0:3], v19 offset:1280
	s_waitcnt lgkmcnt(5)
	v_pk_fma_f32 v[236:237], v[224:225], v[94:95], v[236:237] op_sel_hi:[1,0,1]
	v_pk_fma_f32 v[242:243], v[226:227], v[94:95], v[242:243] op_sel_hi:[1,0,1]
	ds_read_b128 v[220:223], v19 offset:1344
	s_waitcnt lgkmcnt(5)
	v_pk_fma_f32 v[232:233], v[228:229], v[86:87], v[232:233] op_sel_hi:[1,0,1]
	v_pk_fma_f32 v[234:235], v[230:231], v[86:87], v[234:235] op_sel_hi:[1,0,1]
	ds_read_b128 v[224:227], v19 offset:1408
	s_waitcnt lgkmcnt(5)
	v_pk_fma_f32 v[236:237], v[244:245], v[86:87], v[236:237] op_sel:[0,1,0]
	v_pk_fma_f32 v[242:243], v[246:247], v[86:87], v[242:243] op_sel:[0,1,0]
	ds_read_b128 v[228:231], v19 offset:1472
	s_waitcnt lgkmcnt(5)
	v_pk_fma_f32 v[232:233], v[248:249], v[88:89], v[232:233] op_sel_hi:[1,0,1]
	v_pk_fma_f32 v[234:235], v[250:251], v[88:89], v[234:235] op_sel_hi:[1,0,1]
	ds_read_b128 v[244:247], v19 offset:1536
	s_waitcnt lgkmcnt(5)
	v_pk_fma_f32 v[236:237], v[252:253], v[94:95], v[236:237] op_sel:[0,1,0]
	v_pk_fma_f32 v[242:243], v[254:255], v[94:95], v[242:243] op_sel:[0,1,0]
	ds_read_b128 v[248:251], v19 offset:1600
	s_waitcnt lgkmcnt(5)
	v_pk_fma_f32 v[232:233], v[0:1], v[88:89], v[232:233] op_sel:[0,1,0]
	v_pk_fma_f32 v[234:235], v[2:3], v[88:89], v[234:235] op_sel:[0,1,0]
	ds_read_b128 v[252:255], v19 offset:1664
	s_waitcnt lgkmcnt(5)
	v_pk_fma_f32 v[236:237], v[220:221], v[26:27], v[236:237] op_sel_hi:[1,0,1]
	v_pk_fma_f32 v[242:243], v[222:223], v[26:27], v[242:243] op_sel_hi:[1,0,1]
	ds_read_b128 v[0:3], v19 offset:1728
	s_waitcnt lgkmcnt(5)
	v_pk_fma_f32 v[232:233], v[224:225], v[26:27], v[232:233] op_sel:[0,1,0]
	v_pk_fma_f32 v[234:235], v[226:227], v[26:27], v[234:235] op_sel:[0,1,0]
	ds_read_b128 v[220:223], v19 offset:1792
	s_waitcnt lgkmcnt(5)
	v_pk_fma_f32 v[236:237], v[228:229], v[24:25], v[236:237] op_sel_hi:[1,0,1]
	v_pk_fma_f32 v[242:243], v[230:231], v[24:25], v[242:243] op_sel_hi:[1,0,1]
	ds_read_b128 v[224:227], v19 offset:1856
	s_waitcnt lgkmcnt(5)
	v_pk_fma_f32 v[232:233], v[244:245], v[24:25], v[232:233] op_sel:[0,1,0]
	v_pk_fma_f32 v[234:235], v[246:247], v[24:25], v[234:235] op_sel:[0,1,0]
	ds_read_b128 v[228:231], v19 offset:1920
	s_waitcnt lgkmcnt(5)
	v_pk_fma_f32 v[236:237], v[248:249], v[30:31], v[236:237] op_sel_hi:[1,0,1]
	v_pk_fma_f32 v[242:243], v[250:251], v[30:31], v[242:243] op_sel_hi:[1,0,1]
	ds_read_b128 v[244:247], v19 offset:1984
	s_waitcnt lgkmcnt(5)
	v_pk_fma_f32 v[232:233], v[252:253], v[30:31], v[232:233] op_sel:[0,1,0]
	v_pk_fma_f32 v[234:235], v[254:255], v[30:31], v[234:235] op_sel:[0,1,0]
	ds_read_b128 v[248:251], v19 offset:2048
	s_waitcnt lgkmcnt(5)
	v_pk_fma_f32 v[236:237], v[0:1], v[102:103], v[236:237] op_sel:[0,1,0]
	v_pk_fma_f32 v[242:243], v[2:3], v[102:103], v[242:243] op_sel:[0,1,0]
	ds_read_b128 v[252:255], v19 offset:2112
	s_waitcnt lgkmcnt(5)
	v_pk_fma_f32 v[232:233], v[220:221], v[96:97], v[232:233] op_sel_hi:[1,0,1]
	v_pk_fma_f32 v[234:235], v[222:223], v[96:97], v[234:235] op_sel_hi:[1,0,1]
	ds_read_b128 v[0:3], v19 offset:2176
	s_waitcnt lgkmcnt(5)
	v_pk_fma_f32 v[236:237], v[224:225], v[34:35], v[236:237] op_sel_hi:[1,0,1]
	v_pk_fma_f32 v[242:243], v[226:227], v[34:35], v[242:243] op_sel_hi:[1,0,1]
	ds_read_b128 v[220:223], v19 offset:2240
	s_waitcnt lgkmcnt(5)
	v_pk_fma_f32 v[232:233], v[228:229], v[34:35], v[232:233] op_sel:[0,1,0]
	v_pk_fma_f32 v[234:235], v[230:231], v[34:35], v[234:235] op_sel:[0,1,0]
	ds_read_b128 v[224:227], v19 offset:2304
	s_waitcnt lgkmcnt(5)
	v_pk_fma_f32 v[236:237], v[244:245], v[28:29], v[236:237] op_sel_hi:[1,0,1]
	v_pk_fma_f32 v[242:243], v[246:247], v[28:29], v[242:243] op_sel_hi:[1,0,1]
	ds_read_b128 v[228:231], v19 offset:2368
	s_waitcnt lgkmcnt(5)
	v_pk_fma_f32 v[232:233], v[248:249], v[96:97], v[232:233] op_sel:[0,1,0]
	v_pk_fma_f32 v[234:235], v[250:251], v[96:97], v[234:235] op_sel:[0,1,0]
	ds_read_b128 v[244:247], v19 offset:2432
	s_waitcnt lgkmcnt(5)
; __device__ void phase_combine(const P& p, int l, int ntok, float* lds) {
;     ...
; #pragma unroll
;         for (int m = 0; m < 96; m += 4) {
; #pragma unroll
;           for (int i = 0; i < 4; ++i) {
;             float4 s = *reinterpret_cast<const float4*>(sig + (i0 + i) * 96 + m);
;             gate[i] += s.x * g2r[m] + s.y * g2r[m + 1] + s.z * g2r[m + 2] + s.w * g2r[m + 3];
	v_pk_fma_f32 v[236:237], v[252:253], v[38:39], v[236:237] op_sel_hi:[1,0,1]
	v_pk_fma_f32 v[242:243], v[254:255], v[38:39], v[242:243] op_sel_hi:[1,0,1]
	ds_read_b128 v[248:251], v19 offset:2496
	s_waitcnt lgkmcnt(5)
	v_pk_fma_f32 v[232:233], v[0:1], v[38:39], v[232:233] op_sel:[0,1,0]
	v_pk_fma_f32 v[234:235], v[2:3], v[38:39], v[234:235] op_sel:[0,1,0]
	ds_read_b128 v[252:255], v19 offset:2560
	s_waitcnt lgkmcnt(5)
	v_pk_fma_f32 v[236:237], v[220:221], v[28:29], v[236:237] op_sel:[0,1,0]
	v_pk_fma_f32 v[242:243], v[222:223], v[28:29], v[242:243] op_sel:[0,1,0]
	ds_read_b128 v[0:3], v19 offset:2624
	s_waitcnt lgkmcnt(5)
	v_pk_fma_f32 v[232:233], v[224:225], v[98:99], v[232:233] op_sel_hi:[1,0,1]
	v_pk_fma_f32 v[234:235], v[226:227], v[98:99], v[234:235] op_sel_hi:[1,0,1]
	ds_read_b128 v[220:223], v19 offset:2688
	s_waitcnt lgkmcnt(5)
	v_pk_fma_f32 v[236:237], v[228:229], v[42:43], v[236:237] op_sel_hi:[1,0,1]
	v_pk_fma_f32 v[242:243], v[230:231], v[42:43], v[242:243] op_sel_hi:[1,0,1]
	ds_read_b128 v[224:227], v19 offset:2752
	s_waitcnt lgkmcnt(5)
	v_pk_fma_f32 v[232:233], v[244:245], v[42:43], v[232:233] op_sel:[0,1,0]
	v_pk_fma_f32 v[234:235], v[246:247], v[42:43], v[234:235] op_sel:[0,1,0]
	ds_read_b128 v[228:231], v19 offset:2816
	s_waitcnt lgkmcnt(5)
	v_pk_fma_f32 v[236:237], v[248:249], v[36:37], v[236:237] op_sel_hi:[1,0,1]
	v_pk_fma_f32 v[242:243], v[250:251], v[36:37], v[242:243] op_sel_hi:[1,0,1]
	ds_read_b128 v[244:247], v19 offset:2880
	s_waitcnt lgkmcnt(5)
	v_pk_fma_f32 v[232:233], v[252:253], v[98:99], v[232:233] op_sel:[0,1,0]
	v_pk_fma_f32 v[234:235], v[254:255], v[98:99], v[234:235] op_sel:[0,1,0]
	ds_read_b128 v[248:251], v19 offset:2944
	s_waitcnt lgkmcnt(5)
	v_pk_fma_f32 v[236:237], v[0:1], v[46:47], v[236:237] op_sel_hi:[1,0,1]
	v_pk_fma_f32 v[242:243], v[2:3], v[46:47], v[242:243] op_sel_hi:[1,0,1]
	ds_read_b128 v[252:255], v19 offset:3008
	s_waitcnt lgkmcnt(5)
	v_pk_fma_f32 v[232:233], v[220:221], v[46:47], v[232:233] op_sel:[0,1,0]
	v_pk_fma_f32 v[234:235], v[222:223], v[46:47], v[234:235] op_sel:[0,1,0]
	ds_read_b128 v[0:3], v19 offset:3072
	s_waitcnt lgkmcnt(5)
	v_pk_fma_f32 v[236:237], v[224:225], v[36:37], v[236:237] op_sel:[0,1,0]
	v_pk_fma_f32 v[242:243], v[226:227], v[36:37], v[242:243] op_sel:[0,1,0]
	ds_read_b128 v[220:223], v19 offset:3136
	s_waitcnt lgkmcnt(5)
	v_pk_fma_f32 v[232:233], v[228:229], v[100:101], v[232:233] op_sel_hi:[1,0,1]
	v_pk_fma_f32 v[234:235], v[230:231], v[100:101], v[234:235] op_sel_hi:[1,0,1]
	ds_read_b128 v[224:227], v19 offset:3200
	s_waitcnt lgkmcnt(5)
	v_pk_fma_f32 v[236:237], v[244:245], v[50:51], v[236:237] op_sel_hi:[1,0,1]
	v_pk_fma_f32 v[242:243], v[246:247], v[50:51], v[242:243] op_sel_hi:[1,0,1]
	ds_read_b128 v[228:231], v19 offset:3264
	s_waitcnt lgkmcnt(5)
	v_pk_fma_f32 v[232:233], v[248:249], v[50:51], v[232:233] op_sel:[0,1,0]
	v_pk_fma_f32 v[234:235], v[250:251], v[50:51], v[234:235] op_sel:[0,1,0]
	ds_read_b128 v[244:247], v19 offset:3328
	s_waitcnt lgkmcnt(5)
	v_pk_fma_f32 v[236:237], v[252:253], v[40:41], v[236:237] op_sel_hi:[1,0,1]
	v_pk_fma_f32 v[242:243], v[254:255], v[40:41], v[242:243] op_sel_hi:[1,0,1]
	ds_read_b128 v[248:251], v19 offset:3392
	s_waitcnt lgkmcnt(5)
	v_pk_fma_f32 v[232:233], v[0:1], v[100:101], v[232:233] op_sel:[0,1,0]
	v_pk_fma_f32 v[234:235], v[2:3], v[100:101], v[234:235] op_sel:[0,1,0]
	ds_read_b128 v[252:255], v19 offset:3456
	s_waitcnt lgkmcnt(5)
	v_pk_fma_f32 v[236:237], v[220:221], v[56:57], v[236:237] op_sel_hi:[1,0,1]
	v_pk_fma_f32 v[242:243], v[222:223], v[56:57], v[242:243] op_sel_hi:[1,0,1]
	ds_read_b128 v[0:3], v19 offset:3520
	s_waitcnt lgkmcnt(5)
	v_pk_fma_f32 v[232:233], v[224:225], v[56:57], v[232:233] op_sel:[0,1,0]
	v_pk_fma_f32 v[234:235], v[226:227], v[56:57], v[234:235] op_sel:[0,1,0]
	ds_read_b128 v[220:223], v19 offset:3584
	s_waitcnt lgkmcnt(5)
	v_pk_fma_f32 v[236:237], v[228:229], v[40:41], v[236:237] op_sel:[0,1,0]
	v_pk_fma_f32 v[242:243], v[230:231], v[40:41], v[242:243] op_sel:[0,1,0]
	ds_read_b128 v[224:227], v19 offset:3648
	s_waitcnt lgkmcnt(5)
	v_pk_fma_f32 v[232:233], v[244:245], v[102:103], v[232:233] op_sel_hi:[1,0,1]
	v_pk_fma_f32 v[234:235], v[246:247], v[102:103], v[234:235] op_sel_hi:[1,0,1]
	ds_read_b128 v[228:231], v19 offset:3712
	s_waitcnt lgkmcnt(5)
	v_pk_fma_f32 v[236:237], v[248:249], v[60:61], v[236:237] op_sel_hi:[1,0,1]
	v_pk_fma_f32 v[242:243], v[250:251], v[60:61], v[242:243] op_sel_hi:[1,0,1]
	ds_read_b128 v[244:247], v19 offset:3776
	s_waitcnt lgkmcnt(5)
	v_pk_fma_f32 v[232:233], v[252:253], v[60:61], v[232:233] op_sel:[0,1,0]
	v_pk_fma_f32 v[234:235], v[254:255], v[60:61], v[234:235] op_sel:[0,1,0]
	ds_read_b128 v[248:251], v19 offset:3840
	s_waitcnt lgkmcnt(5)
	v_pk_fma_f32 v[236:237], v[0:1], v[44:45], v[236:237] op_sel_hi:[1,0,1]
	v_pk_fma_f32 v[242:243], v[2:3], v[44:45], v[242:243] op_sel_hi:[1,0,1]
	ds_read_b128 v[252:255], v19 offset:3904
	s_waitcnt lgkmcnt(5)
	v_pk_fma_f32 v[232:233], v[220:221], v[44:45], v[232:233] op_sel:[0,1,0]
	v_pk_fma_f32 v[234:235], v[222:223], v[44:45], v[234:235] op_sel:[0,1,0]
	ds_read_b128 v[0:3], v19 offset:3968
	s_waitcnt lgkmcnt(5)
	v_pk_fma_f32 v[236:237], v[224:225], v[48:49], v[236:237] op_sel_hi:[1,0,1]
	v_pk_fma_f32 v[242:243], v[226:227], v[48:49], v[242:243] op_sel_hi:[1,0,1]
	ds_read_b128 v[220:223], v19 offset:4032
	s_waitcnt lgkmcnt(5)
	v_pk_fma_f32 v[232:233], v[228:229], v[48:49], v[232:233] op_sel:[0,1,0]
	v_pk_fma_f32 v[234:235], v[230:231], v[48:49], v[234:235] op_sel:[0,1,0]
	ds_read_b128 v[224:227], v19 offset:4096
	s_waitcnt lgkmcnt(5)
; __device__ void phase_combine(const P& p, int l, int ntok, float* lds) {
;     ...
;         for (int m = 0; m < 96; m += 4) {
; #pragma unroll
;           for (int i = 0; i < 4; ++i) {
;             float4 s = *reinterpret_cast<const float4*>(sig + (i0 + i) * 96 + m);
;             gate[i] += s.x * g2r[m] + s.y * g2r[m + 1] + s.z * g2r[m + 2] + s.w * g2r[m + 3];
;           }
;         }
	v_pk_fma_f32 v[236:237], v[244:245], v[54:55], v[236:237] op_sel_hi:[1,0,1]
	v_pk_fma_f32 v[242:243], v[246:247], v[54:55], v[242:243] op_sel_hi:[1,0,1]
	ds_read_b128 v[228:231], v19 offset:4160
	s_waitcnt lgkmcnt(5)
	v_pk_fma_f32 v[232:233], v[248:249], v[52:53], v[232:233] op_sel_hi:[1,0,1]
	v_pk_fma_f32 v[234:235], v[250:251], v[52:53], v[234:235] op_sel_hi:[1,0,1]
	ds_read_b128 v[244:247], v19 offset:4224
	s_waitcnt lgkmcnt(5)
	v_pk_fma_f32 v[236:237], v[252:253], v[52:53], v[236:237] op_sel:[0,1,0]
	v_pk_fma_f32 v[242:243], v[254:255], v[52:53], v[242:243] op_sel:[0,1,0]
	ds_read_b128 v[248:251], v19 offset:4288
	s_waitcnt lgkmcnt(5)
	v_pk_fma_f32 v[232:233], v[0:1], v[58:59], v[232:233] op_sel_hi:[1,0,1]
	v_pk_fma_f32 v[234:235], v[2:3], v[58:59], v[234:235] op_sel_hi:[1,0,1]
	ds_read_b128 v[252:255], v19 offset:4352
	s_waitcnt lgkmcnt(5)
	v_pk_fma_f32 v[236:237], v[220:221], v[54:55], v[236:237] op_sel:[0,1,0]
	v_pk_fma_f32 v[242:243], v[222:223], v[54:55], v[242:243] op_sel:[0,1,0]
	ds_read_b128 v[0:3], v19 offset:4416
	s_waitcnt lgkmcnt(5)
	v_pk_fma_f32 v[232:233], v[224:225], v[58:59], v[232:233] op_sel:[0,1,0]
	v_pk_fma_f32 v[234:235], v[226:227], v[58:59], v[234:235] op_sel:[0,1,0]
	ds_read_b128 v[220:223], v19 offset:4480
	s_waitcnt lgkmcnt(5)
	v_pk_fma_f32 v[236:237], v[228:229], v[64:65], v[236:237] op_sel_hi:[1,0,1]
	v_pk_fma_f32 v[242:243], v[230:231], v[64:65], v[242:243] op_sel_hi:[1,0,1]
	ds_read_b128 v[224:227], v19 offset:4544
	s_waitcnt lgkmcnt(5)
	v_pk_fma_f32 v[232:233], v[244:245], v[64:65], v[232:233] op_sel:[0,1,0]
	v_pk_fma_f32 v[234:235], v[246:247], v[64:65], v[234:235] op_sel:[0,1,0]
	ds_read_b128 v[228:231], v19 offset:4608
	s_waitcnt lgkmcnt(5)
	v_pk_fma_f32 v[236:237], v[248:249], v[62:63], v[236:237] op_sel_hi:[1,0,1]
	v_pk_fma_f32 v[242:243], v[250:251], v[62:63], v[242:243] op_sel_hi:[1,0,1]
	ds_read_b128 v[244:247], v19 offset:4672
	s_waitcnt lgkmcnt(5)
	v_pk_fma_f32 v[232:233], v[252:253], v[66:67], v[232:233] op_sel_hi:[1,0,1]
	v_pk_fma_f32 v[234:235], v[254:255], v[66:67], v[234:235] op_sel_hi:[1,0,1]
	ds_read_b128 v[248:251], v19 offset:4736
	s_waitcnt lgkmcnt(5)
	v_pk_fma_f32 v[236:237], v[0:1], v[66:67], v[236:237] op_sel:[0,1,0]
	v_pk_fma_f32 v[242:243], v[2:3], v[66:67], v[242:243] op_sel:[0,1,0]
	ds_read_b128 v[252:255], v19 offset:4800
	s_waitcnt lgkmcnt(5)
	v_pk_fma_f32 v[232:233], v[220:221], v[70:71], v[232:233] op_sel_hi:[1,0,1]
	v_pk_fma_f32 v[234:235], v[222:223], v[70:71], v[234:235] op_sel_hi:[1,0,1]
	ds_read_b128 v[0:3], v19 offset:4864
	s_waitcnt lgkmcnt(5)
	v_pk_fma_f32 v[236:237], v[224:225], v[62:63], v[236:237] op_sel:[0,1,0]
	v_pk_fma_f32 v[242:243], v[226:227], v[62:63], v[242:243] op_sel:[0,1,0]
	ds_read_b128 v[220:223], v19 offset:4928
	s_waitcnt lgkmcnt(5)
	v_pk_fma_f32 v[232:233], v[228:229], v[70:71], v[232:233] op_sel:[0,1,0]
	v_pk_fma_f32 v[234:235], v[230:231], v[70:71], v[234:235] op_sel:[0,1,0]
	ds_read_b128 v[224:227], v19 offset:4992
	s_waitcnt lgkmcnt(5)
	v_pk_fma_f32 v[236:237], v[244:245], v[74:75], v[236:237] op_sel_hi:[1,0,1]
	v_pk_fma_f32 v[242:243], v[246:247], v[74:75], v[242:243] op_sel_hi:[1,0,1]
	ds_read_b128 v[228:231], v19 offset:5056
	s_waitcnt lgkmcnt(5)
	v_pk_fma_f32 v[232:233], v[248:249], v[74:75], v[232:233] op_sel:[0,1,0]
	v_pk_fma_f32 v[234:235], v[250:251], v[74:75], v[234:235] op_sel:[0,1,0]
	ds_read_b128 v[244:247], v19 offset:5120
	s_waitcnt lgkmcnt(5)
	v_pk_fma_f32 v[236:237], v[252:253], v[68:69], v[236:237] op_sel_hi:[1,0,1]
	v_pk_fma_f32 v[242:243], v[254:255], v[68:69], v[242:243] op_sel_hi:[1,0,1]
	ds_read_b128 v[248:251], v19 offset:5184
	s_waitcnt lgkmcnt(5)
	v_pk_fma_f32 v[232:233], v[0:1], v[104:105], v[232:233] op_sel_hi:[1,0,1]
	v_pk_fma_f32 v[234:235], v[2:3], v[104:105], v[234:235] op_sel_hi:[1,0,1]
	ds_read_b128 v[252:255], v19 offset:5248
	s_waitcnt lgkmcnt(5)
	v_pk_fma_f32 v[236:237], v[220:221], v[104:105], v[236:237] op_sel:[0,1,0]
	v_pk_fma_f32 v[242:243], v[222:223], v[104:105], v[242:243] op_sel:[0,1,0]
	ds_read_b128 v[0:3], v19 offset:5312
	s_waitcnt lgkmcnt(5)
	v_pk_fma_f32 v[232:233], v[224:225], v[106:107], v[232:233] op_sel_hi:[1,0,1]
	v_pk_fma_f32 v[234:235], v[226:227], v[106:107], v[234:235] op_sel_hi:[1,0,1]
	ds_read_b128 v[220:223], v19 offset:5376
	s_waitcnt lgkmcnt(5)
	v_pk_fma_f32 v[236:237], v[228:229], v[68:69], v[236:237] op_sel:[0,1,0]
	v_pk_fma_f32 v[242:243], v[230:231], v[68:69], v[242:243] op_sel:[0,1,0]
	ds_read_b128 v[224:227], v19 offset:5440
	s_waitcnt lgkmcnt(5)
	v_pk_fma_f32 v[232:233], v[244:245], v[106:107], v[232:233] op_sel:[0,1,0]
	v_pk_fma_f32 v[234:235], v[246:247], v[106:107], v[234:235] op_sel:[0,1,0]
	ds_read_b128 v[228:231], v19 offset:5504
	s_waitcnt lgkmcnt(5)
	v_pk_fma_f32 v[236:237], v[248:249], v[108:109], v[236:237] op_sel_hi:[1,0,1]
	v_pk_fma_f32 v[242:243], v[250:251], v[108:109], v[242:243] op_sel_hi:[1,0,1]
	ds_read_b128 v[244:247], v19 offset:5568
	s_waitcnt lgkmcnt(5)
	v_pk_fma_f32 v[232:233], v[252:253], v[108:109], v[232:233] op_sel:[0,1,0]
	v_pk_fma_f32 v[234:235], v[254:255], v[108:109], v[234:235] op_sel:[0,1,0]
	ds_read_b128 v[248:251], v19 offset:5632
	s_waitcnt lgkmcnt(5)
	v_pk_fma_f32 v[236:237], v[0:1], v[72:73], v[236:237] op_sel_hi:[1,0,1]
	v_pk_fma_f32 v[242:243], v[2:3], v[72:73], v[242:243] op_sel_hi:[1,0,1]
	ds_read_b128 v[252:255], v19 offset:5696
	s_waitcnt lgkmcnt(5)
	v_pk_fma_f32 v[232:233], v[220:221], v[110:111], v[232:233] op_sel_hi:[1,0,1]
	v_pk_fma_f32 v[234:235], v[222:223], v[110:111], v[234:235] op_sel_hi:[1,0,1]
	ds_read_b128 v[0:3], v19 offset:5760
	s_waitcnt lgkmcnt(5)
; __device__ __forceinline__ float bf2f(u16 v) { return __uint_as_float(((unsigned)v) << 16); }
; __device__ void phase_combine(const P& p, int l, int ntok, float* lds) {
;     ...
;         for (int m = 0; m < 96; m += 4) {
; #pragma unroll
;           for (int i = 0; i < 4; ++i) {
;             float4 s = *reinterpret_cast<const float4*>(sig + (i0 + i) * 96 + m);
;             gate[i] += s.x * g2r[m] + s.y * g2r[m + 1] + s.z * g2r[m + 2] + s.w * g2r[m + 3];
;           }
;         }
; #pragma unroll
;         for (int i = 0; i < 4; ++i) {
;           int row = r0 + i0 + i, t = tb + i0 + i;
;           float yv = bf2f((u16)y0[i]) + bf2f((u16)y1[i]);
;           float mean = wave_sum_b(yv) * (1.f / 64.f);
;           float d = yv - mean;
;           float var = wave_sum_b(d * d) * (1.f / 64.f);
;           float yn = d * rsqrtf(var + 64e-5f) * gnw + gnb;
;           float v_c = bf2f((u16)vc[i]), v_p = t > 0 ? bf2f((u16)vp[i]) : 0.f, v_n = t < T - 1 ? bf2f((u16)vn[i]) : 0.f;
;           float vf = v_c + (v_p - v_c) * muvf, vb = v_c + (v_n - v_c) * muvb;
;           float bonus = sf[i] * vf + sb[i] * vb;
;           p.nbuf[(size_t)row * D + 1536 + tid] = f2bf((yn + bonus) * gate[i]);
;         }
	v_pk_fma_f32 v[236:237], v[224:225], v[110:111], v[236:237] op_sel:[0,1,0]
	v_pk_fma_f32 v[242:243], v[226:227], v[110:111], v[242:243] op_sel:[0,1,0]
	ds_read_b128 v[220:223], v19 offset:5824
	s_waitcnt lgkmcnt(5)
	v_pk_fma_f32 v[232:233], v[228:229], v[112:113], v[232:233] op_sel_hi:[1,0,1]
	v_pk_fma_f32 v[234:235], v[230:231], v[112:113], v[234:235] op_sel_hi:[1,0,1]
	ds_read_b128 v[224:227], v19 offset:5888
	s_waitcnt lgkmcnt(5)
	v_pk_fma_f32 v[236:237], v[244:245], v[72:73], v[236:237] op_sel:[0,1,0]
	v_pk_fma_f32 v[242:243], v[246:247], v[72:73], v[242:243] op_sel:[0,1,0]
	ds_read_b128 v[228:231], v19 offset:5952
	s_waitcnt lgkmcnt(5)
	v_pk_fma_f32 v[232:233], v[248:249], v[76:77], v[232:233] op_sel_hi:[1,0,1]
	v_pk_fma_f32 v[234:235], v[250:251], v[76:77], v[234:235] op_sel_hi:[1,0,1]
	ds_read_b128 v[244:247], v19 offset:6016
	s_waitcnt lgkmcnt(5)
	v_pk_fma_f32 v[236:237], v[252:253], v[76:77], v[236:237] op_sel:[0,1,0]
	v_pk_fma_f32 v[242:243], v[254:255], v[76:77], v[242:243] op_sel:[0,1,0]
	ds_read_b128 v[248:251], v19 offset:6080
	s_waitcnt lgkmcnt(5)
	v_pk_fma_f32 v[232:233], v[0:1], v[112:113], v[232:233] op_sel:[0,1,0]
	v_pk_fma_f32 v[234:235], v[2:3], v[112:113], v[234:235] op_sel:[0,1,0]
	s_waitcnt lgkmcnt(4)
	v_pk_fma_f32 v[236:237], v[220:221], v[116:117], v[236:237] op_sel_hi:[1,0,1]
	v_pk_fma_f32 v[242:243], v[222:223], v[116:117], v[242:243] op_sel_hi:[1,0,1]
	s_waitcnt lgkmcnt(3)
	v_pk_fma_f32 v[232:233], v[224:225], v[114:115], v[232:233] op_sel_hi:[1,0,1]
	v_pk_fma_f32 v[234:235], v[226:227], v[114:115], v[234:235] op_sel_hi:[1,0,1]
	s_waitcnt lgkmcnt(2)
	v_pk_fma_f32 v[236:237], v[228:229], v[114:115], v[236:237] op_sel:[0,1,0]
	v_pk_fma_f32 v[242:243], v[230:231], v[114:115], v[242:243] op_sel:[0,1,0]
	s_waitcnt lgkmcnt(1)
	v_pk_fma_f32 v[232:233], v[244:245], v[116:117], v[232:233] op_sel:[0,1,0]
	v_pk_fma_f32 v[234:235], v[246:247], v[116:117], v[234:235] op_sel:[0,1,0]
	s_waitcnt lgkmcnt(0)
	v_pk_fma_f32 v[236:237], v[248:249], v[118:119], v[236:237] op_sel_hi:[1,0,1]
	v_pk_fma_f32 v[242:243], v[250:251], v[118:119], v[242:243] op_sel_hi:[1,0,1]
	v_pk_add_f32 v[232:233], v[232:233], v[236:237]
	v_pk_add_f32 v[234:235], v[234:235], v[242:243]
	s_nop 0
	v_mov_b32_e32 v221, v232
	v_mov_b32_e32 v222, v233
	v_mov_b32_e32 v223, v234
	v_mov_b32_e32 v0, v235
	s_waitcnt vmcnt(30)
	s_waitcnt vmcnt(29)
	s_waitcnt vmcnt(4)
	s_waitcnt vmcnt(0)
	v_lshlrev_b32_e32 v197, 16, v197
	v_lshlrev_b32_e32 v192, 16, v192
	v_lshlrev_b32_e32 v164, 16, v164
	v_lshlrev_b32_e32 v158, 16, v158
	v_lshlrev_b32_e32 v152, 16, v152
	v_lshlrev_b32_e32 v138, 16, v138
	v_lshlrev_b32_e32 v1, 16, v201
	v_lshlrev_b32_e32 v2, 16, v202
	v_add_f32_e32 v1, v2, v1
	v_mov_b32_e32 v3, v129
	s_nop 0
	v_add_f32_dpp v2, v1, v1 quad_perm:[1,0,3,2] row_mask:0xf bank_mask:0xf bound_ctrl:1
	s_nop 1
	v_add_f32_dpp v2, v2, v2 quad_perm:[2,3,0,1] row_mask:0xf bank_mask:0xf bound_ctrl:1
	s_nop 1
	v_add_f32_dpp v2, v2, v2 row_half_mirror row_mask:0xf bank_mask:0xf bound_ctrl:1
	s_nop 1
	v_add_f32_dpp v2, v2, v2 row_mirror row_mask:0xf bank_mask:0xf bound_ctrl:1
	s_nop 1
	v_mov_b32_dpp v3, v2 row_bcast:15 row_mask:0xa bank_mask:0xf
	v_add_f32_e32 v2, v2, v3
	v_mov_b32_e32 v3, v129
	s_nop 1
	v_mov_b32_dpp v3, v2 row_bcast:31 row_mask:0xc bank_mask:0xf
	v_add_f32_e32 v2, v2, v3
	v_mov_b32_e32 v3, v129
	v_readlane_b32 s0, v2, 63
	s_nop 1
	v_fmac_f32_e32 v1, s0, v180
	v_mul_f32_e32 v2, v1, v1
	s_nop 1
	v_mov_b32_dpp v2, v2 quad_perm:[1,0,3,2] row_mask:0xf bank_mask:0xf bound_ctrl:1
	v_fmac_f32_e32 v2, v1, v1
	s_nop 1
	v_add_f32_dpp v2, v2, v2 quad_perm:[2,3,0,1] row_mask:0xf bank_mask:0xf bound_ctrl:1
	s_nop 1
	v_add_f32_dpp v2, v2, v2 row_half_mirror row_mask:0xf bank_mask:0xf bound_ctrl:1
	s_nop 1
	v_add_f32_dpp v2, v2, v2 row_mirror row_mask:0xf bank_mask:0xf bound_ctrl:1
	s_nop 1
	v_mov_b32_dpp v3, v2 row_bcast:15 row_mask:0xa bank_mask:0xf
	v_add_f32_e32 v2, v2, v3
	v_mov_b32_e32 v3, v129
	s_nop 1
	v_mov_b32_dpp v3, v2 row_bcast:31 row_mask:0xc bank_mask:0xf
	v_add_f32_e32 v2, v2, v3
	s_nop 0
	v_readlane_b32 s0, v2, 63
	s_nop 1
	v_fma_f32 v2, s0, v181, v170
	v_cmp_gt_f32_e64 s[0:1], s33, v2
	v_mul_f32_e32 v3, 0x4b800000, v2
	s_nop 0
	v_cndmask_b32_e64 v2, v2, v3, s[0:1]
	v_rsq_f32_e32 v2, v2
	s_nop 0
	v_mul_f32_e32 v3, 0x45800000, v2
	v_cndmask_b32_e64 v2, v2, v3, s[0:1]
	v_mul_f32_e32 v1, v1, v2
	v_lshlrev_b32_e32 v2, 16, v18
	v_lshlrev_b32_e32 v3, 16, v208
	v_lshlrev_b32_e32 v18, 16, v210
	v_cndmask_b32_e64 v3, v3, 0, s[52:53]
	v_cndmask_b32_e64 v18, 0, v18, s[44:45]
	v_sub_f32_e32 v3, v3, v2
	v_sub_f32_e32 v18, v18, v2
	v_fma_f32 v3, v121, v3, v2
	v_fmac_f32_e32 v2, v122, v18
	v_mul_f32_e32 v2, v219, v2
	v_fma_f32 v1, v119, v1, v120
	v_fmac_f32_e32 v2, v218, v3
	v_add_f32_e32 v1, v2, v1
	v_mul_f32_e32 v1, v221, v1
	v_bfe_u32 v2, v1, 16, 1
	s_lshl_b64 s[44:45], s[46:47], 12
	v_add3_u32 v1, v1, v2, s21
	v_lshl_add_u64 v[18:19], v[14:15], 0, s[44:45]
	global_store_short_d16_hi v[18:19], v1, off offset:3072
	v_lshlrev_b32_e32 v1, 16, v212
	v_lshlrev_b32_e32 v2, 16, v213
	v_add_f32_e32 v1, v2, v1
	v_mov_b32_e32 v3, v129
	s_nop 0
	v_add_f32_dpp v2, v1, v1 quad_perm:[1,0,3,2] row_mask:0xf bank_mask:0xf bound_ctrl:1
	s_nop 1
	v_add_f32_dpp v2, v2, v2 quad_perm:[2,3,0,1] row_mask:0xf bank_mask:0xf bound_ctrl:1
	s_nop 1
	v_add_f32_dpp v2, v2, v2 row_half_mirror row_mask:0xf bank_mask:0xf bound_ctrl:1
	s_nop 1
	v_add_f32_dpp v2, v2, v2 row_mirror row_mask:0xf bank_mask:0xf bound_ctrl:1
	s_nop 1
	v_mov_b32_dpp v3, v2 row_bcast:15 row_mask:0xa bank_mask:0xf
	v_add_f32_e32 v2, v2, v3
	v_mov_b32_e32 v3, v129
	s_nop 1
	v_mov_b32_dpp v3, v2 row_bcast:31 row_mask:0xc bank_mask:0xf
; __device__ __forceinline__ float bf2f(u16 v) { return __uint_as_float(((unsigned)v) << 16); }
; __device__ void phase_combine(const P& p, int l, int ntok, float* lds) {
;     ...
; #pragma unroll
;         for (int i = 0; i < 4; ++i) {
;           int row = r0 + i0 + i, t = tb + i0 + i;
;           float yv = bf2f((u16)y0[i]) + bf2f((u16)y1[i]);
;           float mean = wave_sum_b(yv) * (1.f / 64.f);
;           float d = yv - mean;
;           float var = wave_sum_b(d * d) * (1.f / 64.f);
;           float yn = d * rsqrtf(var + 64e-5f) * gnw + gnb;
;           float v_c = bf2f((u16)vc[i]), v_p = t > 0 ? bf2f((u16)vp[i]) : 0.f, v_n = t < T - 1 ? bf2f((u16)vn[i]) : 0.f;
;           float vf = v_c + (v_p - v_c) * muvf, vb = v_c + (v_n - v_c) * muvb;
;           float bonus = sf[i] * vf + sb[i] * vb;
;           p.nbuf[(size_t)row * D + 1536 + tid] = f2bf((yn + bonus) * gate[i]);
;         }
	v_add_f32_e32 v2, v2, v3
	v_mov_b32_e32 v3, v129
	v_readlane_b32 s0, v2, 63
	s_nop 1
	v_fmac_f32_e32 v1, s0, v180
	v_mul_f32_e32 v2, v1, v1
	s_nop 1
	v_mov_b32_dpp v2, v2 quad_perm:[1,0,3,2] row_mask:0xf bank_mask:0xf bound_ctrl:1
	v_fmac_f32_e32 v2, v1, v1
	s_nop 1
	v_add_f32_dpp v2, v2, v2 quad_perm:[2,3,0,1] row_mask:0xf bank_mask:0xf bound_ctrl:1
	s_nop 1
	v_add_f32_dpp v2, v2, v2 row_half_mirror row_mask:0xf bank_mask:0xf bound_ctrl:1
	s_nop 1
	v_add_f32_dpp v2, v2, v2 row_mirror row_mask:0xf bank_mask:0xf bound_ctrl:1
	s_nop 1
	v_mov_b32_dpp v3, v2 row_bcast:15 row_mask:0xa bank_mask:0xf
	v_add_f32_e32 v2, v2, v3
	v_mov_b32_e32 v3, v129
	s_nop 1
	v_mov_b32_dpp v3, v2 row_bcast:31 row_mask:0xc bank_mask:0xf
	v_add_f32_e32 v2, v2, v3
	s_nop 0
	v_readlane_b32 s0, v2, 63
	s_nop 1
	v_fma_f32 v2, s0, v181, v170
	v_cmp_gt_f32_e64 s[0:1], s33, v2
	v_mul_f32_e32 v3, 0x4b800000, v2
	s_nop 0
	v_cndmask_b32_e64 v2, v2, v3, s[0:1]
	v_rsq_f32_e32 v2, v2
	s_nop 0
	v_mul_f32_e32 v3, 0x45800000, v2
	v_cndmask_b32_e64 v2, v2, v3, s[0:1]
	v_mul_f32_e32 v1, v1, v2
	v_lshlrev_b32_e32 v2, 16, v21
	v_lshlrev_b32_e32 v21, 16, v206
	v_lshlrev_b32_e32 v3, 16, v199
	v_cndmask_b32_e64 v21, 0, v21, s[42:43]
	v_sub_f32_e32 v3, v3, v2
	v_sub_f32_e32 v21, v21, v2
	v_fma_f32 v3, v121, v3, v2
	v_fmac_f32_e32 v2, v122, v21
	v_mul_f32_e32 v2, v20, v2
	v_fma_f32 v1, v119, v1, v120
	v_fmac_f32_e32 v2, v217, v3
	v_add_f32_e32 v1, v2, v1
	v_mul_f32_e32 v1, v222, v1
	v_bfe_u32 v2, v1, 16, 1
	s_lshl_b64 s[42:43], s[50:51], 12
	v_add3_u32 v1, v1, v2, s21
	v_lshl_add_u64 v[20:21], v[14:15], 0, s[42:43]
	global_store_short_d16_hi v[20:21], v1, off offset:3072
	v_lshlrev_b32_e32 v1, 16, v209
	v_lshlrev_b32_e32 v2, 16, v211
	v_add_f32_e32 v1, v2, v1
	v_mov_b32_e32 v3, v129
	s_nop 0
	v_add_f32_dpp v2, v1, v1 quad_perm:[1,0,3,2] row_mask:0xf bank_mask:0xf bound_ctrl:1
	s_nop 1
	v_add_f32_dpp v2, v2, v2 quad_perm:[2,3,0,1] row_mask:0xf bank_mask:0xf bound_ctrl:1
	s_nop 1
	v_add_f32_dpp v2, v2, v2 row_half_mirror row_mask:0xf bank_mask:0xf bound_ctrl:1
	s_nop 1
	v_add_f32_dpp v2, v2, v2 row_mirror row_mask:0xf bank_mask:0xf bound_ctrl:1
	s_nop 1
	v_mov_b32_dpp v3, v2 row_bcast:15 row_mask:0xa bank_mask:0xf
	v_add_f32_e32 v2, v2, v3
	v_mov_b32_e32 v3, v129
	s_nop 1
	v_mov_b32_dpp v3, v2 row_bcast:31 row_mask:0xc bank_mask:0xf
	v_add_f32_e32 v2, v2, v3
	v_mov_b32_e32 v3, v129
	v_readlane_b32 s0, v2, 63
	s_nop 1
	v_fmac_f32_e32 v1, s0, v180
	v_mul_f32_e32 v2, v1, v1
	s_nop 1
	v_mov_b32_dpp v2, v2 quad_perm:[1,0,3,2] row_mask:0xf bank_mask:0xf bound_ctrl:1
	v_fmac_f32_e32 v2, v1, v1
	s_nop 1
	v_add_f32_dpp v2, v2, v2 quad_perm:[2,3,0,1] row_mask:0xf bank_mask:0xf bound_ctrl:1
	s_nop 1
	v_add_f32_dpp v2, v2, v2 row_half_mirror row_mask:0xf bank_mask:0xf bound_ctrl:1
	s_nop 1
	v_add_f32_dpp v2, v2, v2 row_mirror row_mask:0xf bank_mask:0xf bound_ctrl:1
	s_nop 1
	v_mov_b32_dpp v3, v2 row_bcast:15 row_mask:0xa bank_mask:0xf
	v_add_f32_e32 v2, v2, v3
	v_mov_b32_e32 v3, v129
	s_nop 1
	v_mov_b32_dpp v3, v2 row_bcast:31 row_mask:0xc bank_mask:0xf
	v_add_f32_e32 v2, v2, v3
	s_nop 0
	v_readlane_b32 s0, v2, 63
	s_nop 1
	v_fma_f32 v2, s0, v181, v170
	v_cmp_gt_f32_e64 s[0:1], s33, v2
	v_mul_f32_e32 v3, 0x4b800000, v2
	s_nop 0
	v_cndmask_b32_e64 v2, v2, v3, s[0:1]
	v_rsq_f32_e32 v2, v2
	s_nop 0
	v_mul_f32_e32 v3, 0x45800000, v2
	v_cndmask_b32_e64 v2, v2, v3, s[0:1]
	v_lshlrev_b32_e32 v3, 16, v198
	v_lshlrev_b32_e32 v198, 16, v204
	v_mul_f32_e32 v1, v1, v2
	v_lshlrev_b32_e32 v2, 16, v216
	v_cndmask_b32_e64 v198, 0, v198, s[40:41]
	v_sub_f32_e32 v3, v3, v2
	v_sub_f32_e32 v198, v198, v2
	v_fma_f32 v3, v121, v3, v2
	v_fmac_f32_e32 v2, v122, v198
	v_mul_f32_e32 v2, v23, v2
	v_fma_f32 v1, v119, v1, v120
	v_fmac_f32_e32 v2, v215, v3
	v_add_f32_e32 v1, v2, v1
	v_mul_f32_e32 v1, v223, v1
	v_bfe_u32 v2, v1, 16, 1
	v_add3_u32 v1, v1, v2, s21
	v_lshl_add_u64 v[2:3], v[14:15], 0, s[2:3]
	global_store_short_d16_hi v[2:3], v1, off offset:3072
	v_lshlrev_b32_e32 v1, 16, v205
	v_lshlrev_b32_e32 v23, 16, v207
	v_add_f32_e32 v1, v23, v1
	v_mov_b32_e32 v198, v129
	s_nop 0
	v_add_f32_dpp v23, v1, v1 quad_perm:[1,0,3,2] row_mask:0xf bank_mask:0xf bound_ctrl:1
	s_nop 1
	v_add_f32_dpp v23, v23, v23 quad_perm:[2,3,0,1] row_mask:0xf bank_mask:0xf bound_ctrl:1
	s_nop 1
	v_add_f32_dpp v23, v23, v23 row_half_mirror row_mask:0xf bank_mask:0xf bound_ctrl:1
	s_nop 1
	v_add_f32_dpp v23, v23, v23 row_mirror row_mask:0xf bank_mask:0xf bound_ctrl:1
	s_nop 1
	v_mov_b32_dpp v198, v23 row_bcast:15 row_mask:0xa bank_mask:0xf
	v_add_f32_e32 v23, v23, v198
	v_mov_b32_e32 v198, v129
	s_nop 1
	v_mov_b32_dpp v198, v23 row_bcast:31 row_mask:0xc bank_mask:0xf
	v_add_f32_e32 v23, v23, v198
	v_mov_b32_e32 v198, v129
	v_readlane_b32 s0, v23, 63
	s_nop 1
	v_fmac_f32_e32 v1, s0, v180
	v_mul_f32_e32 v23, v1, v1
	s_nop 1
	v_mov_b32_dpp v23, v23 quad_perm:[1,0,3,2] row_mask:0xf bank_mask:0xf bound_ctrl:1
	v_fmac_f32_e32 v23, v1, v1
	s_nop 1
	v_add_f32_dpp v23, v23, v23 quad_perm:[2,3,0,1] row_mask:0xf bank_mask:0xf bound_ctrl:1
	s_nop 1
	v_add_f32_dpp v23, v23, v23 row_half_mirror row_mask:0xf bank_mask:0xf bound_ctrl:1
	s_nop 1
	v_add_f32_dpp v23, v23, v23 row_mirror row_mask:0xf bank_mask:0xf bound_ctrl:1
	s_nop 1
	v_mov_b32_dpp v198, v23 row_bcast:15 row_mask:0xa bank_mask:0xf
	v_add_f32_e32 v23, v23, v198
	v_mov_b32_e32 v198, v129
	s_nop 1
	v_mov_b32_dpp v198, v23 row_bcast:31 row_mask:0xc bank_mask:0xf
	v_add_f32_e32 v23, v23, v198
	s_nop 0
	v_readlane_b32 s0, v23, 63
	s_nop 1
	v_fma_f32 v23, s0, v181, v170
	v_cmp_gt_f32_e64 s[0:1], s33, v23
	v_mul_f32_e32 v198, 0x4b800000, v23
	s_nop 0
	v_cndmask_b32_e64 v23, v23, v198, s[0:1]
	v_rsq_f32_e32 v23, v23
; __device__ __forceinline__ float bf2f(u16 v) { return __uint_as_float(((unsigned)v) << 16); }
; __device__ __forceinline__ float siluf_(float x) { return x / (1.f + __expf(-x)); }
; __device__ void phase_combine(const P& p, int l, int ntok, float* lds) {
;     ...
; #pragma unroll
;         for (int i = 0; i < 4; ++i) {
;           int row = r0 + i0 + i, t = tb + i0 + i;
;           float yv = bf2f((u16)y0[i]) + bf2f((u16)y1[i]);
;           float mean = wave_sum_b(yv) * (1.f / 64.f);
;           float d = yv - mean;
;           float var = wave_sum_b(d * d) * (1.f / 64.f);
;           float yn = d * rsqrtf(var + 64e-5f) * gnw + gnb;
;           float v_c = bf2f((u16)vc[i]), v_p = t > 0 ? bf2f((u16)vp[i]) : 0.f, v_n = t < T - 1 ? bf2f((u16)vn[i]) : 0.f;
;           float vf = v_c + (v_p - v_c) * muvf, vb = v_c + (v_n - v_c) * muvb;
;           float bonus = sf[i] * vf + sb[i] * vb;
;           p.nbuf[(size_t)row * D + 1536 + tid] = f2bf((yn + bonus) * gate[i]);
;         }
;       }
; #pragma unroll
;       for (int i = 0; i < 4; ++i) {
;         int row = r0 + i0 + i;
;         float o0 = bf2f((u16)a0[i]) + bf2f((u16)a1[i]), o1 = bf2f((u16)a2[i]) + bf2f((u16)a3[i]);
;         float ss = wave_sum_b(o0 * o0 + o1 * o1);
;         float rstd = rsqrtf(ss * (1.f / 128.f) + 1e-6f);
;         u16* dst = p.nbuf + (size_t)row * D + mixer * 512 + hh * 128 + lane;
;         dst[0] = f2bf(o0 * rstd * ng0 * siluf_(bf2f((u16)g0r[i])));
;         dst[64] = f2bf(o1 * rstd * ng1 * siluf_(bf2f((u16)g1r[i])));
;       }
	s_nop 0
	v_mul_f32_e32 v198, 0x45800000, v23
	v_cndmask_b32_e64 v23, v23, v198, s[0:1]
	v_lshlrev_b32_e32 v198, 16, v203
	v_mul_f32_e32 v1, v1, v23
	v_lshlrev_b32_e32 v23, 16, v200
	v_cndmask_b32_e32 v198, 0, v198, vcc
	v_sub_f32_e32 v197, v197, v23
	v_sub_f32_e32 v198, v198, v23
	v_fma_f32 v197, v121, v197, v23
	v_fmac_f32_e32 v23, v122, v198
	v_mul_f32_e32 v22, v22, v23
	v_fma_f32 v1, v119, v1, v120
	v_fmac_f32_e32 v22, v214, v197
	v_add_f32_e32 v1, v22, v1
	v_mul_f32_e32 v0, v0, v1
	v_bfe_u32 v1, v0, 16, 1
	s_lshl_b64 s[0:1], s[36:37], 12
	v_add3_u32 v22, v0, v1, s21
	v_lshl_add_u64 v[0:1], v[14:15], 0, s[0:1]
	global_store_short_d16_hi v[0:1], v22, off offset:3072
	v_lshlrev_b32_e32 v22, 16, v195
	v_lshlrev_b32_e32 v23, 16, v196
	v_lshlrev_b32_e32 v196, 16, v193
	v_lshlrev_b32_e32 v197, 16, v194
	v_pk_add_f32 v[22:23], v[22:23], v[196:197]
	v_mul_f32_e32 v196, 0xbfb8aa3b, v192
	v_pk_mul_f32 v[194:195], v[22:23], v[22:23]
	v_exp_f32_e32 v196, v196
	v_add_f32_e32 v193, v194, v195
	v_mov_b32_e32 v194, v129
	v_add_f32_e32 v196, 1.0, v196
	v_add_f32_dpp v193, v193, v193 quad_perm:[1,0,3,2] row_mask:0xf bank_mask:0xf bound_ctrl:1
	s_nop 0
	s_nop 0
	v_add_f32_dpp v193, v193, v193 quad_perm:[2,3,0,1] row_mask:0xf bank_mask:0xf bound_ctrl:1
	s_nop 0
	s_nop 0
	v_add_f32_dpp v193, v193, v193 row_half_mirror row_mask:0xf bank_mask:0xf bound_ctrl:1
	s_nop 0
	s_nop 0
	v_add_f32_dpp v193, v193, v193 row_mirror row_mask:0xf bank_mask:0xf bound_ctrl:1
	s_nop 0
	s_nop 0
	v_mov_b32_dpp v194, v193 row_bcast:15 row_mask:0xa bank_mask:0xf
	v_add_f32_e32 v193, v193, v194
	v_mov_b32_e32 v194, v129
	s_nop 1
	v_mov_b32_dpp v194, v193 row_bcast:31 row_mask:0xc bank_mask:0xf
	v_add_f32_e32 v193, v193, v194
	s_nop 0
	v_readlane_b32 s20, v193, 63
	s_nop 1
	v_fma_f32 v193, s20, v182, v169
	v_cmp_gt_f32_e32 vcc, s33, v193
	v_mul_f32_e32 v194, 0x4b800000, v193
	s_nop 0
	v_cndmask_b32_e32 v193, v193, v194, vcc
	v_rsq_f32_e32 v193, v193
	s_nop 0
	v_mul_f32_e32 v194, 0x45800000, v193
	v_cndmask_b32_e32 v193, v193, v194, vcc
	v_mul_f32_e32 v22, v22, v193
	v_mul_f32_e32 v22, v126, v22
	v_rcp_f32_e32 v197, v196
	s_nop 0
	v_mul_f32_e32 v192, v192, v197
	v_mul_f32_e32 v22, v192, v22
	v_bfe_u32 v192, v22, 16, 1
	v_lshl_add_u64 v[194:195], v[12:13], 0, s[44:45]
	v_add3_u32 v22, v22, v192, s21
	global_store_short_d16_hi v[194:195], v22, off
	v_mul_f32_e32 v22, v23, v193
	v_lshlrev_b32_e32 v23, 16, v191
	v_mul_f32_e32 v191, 0xbfb8aa3b, v23
	v_exp_f32_e32 v191, v191
	v_mul_f32_e32 v22, v127, v22
	v_add_f32_e32 v191, 1.0, v191
	s_nop 0
	v_rcp_f32_e32 v192, v191
	s_nop 0
	v_mul_f32_e32 v23, v23, v192
	v_mul_f32_e32 v22, v23, v22
	v_bfe_u32 v23, v22, 16, 1
	v_add3_u32 v22, v22, v23, s21
	global_store_short_d16_hi v[194:195], v22, off offset:128
	v_lshlrev_b32_e32 v22, 16, v167
	v_lshlrev_b32_e32 v23, 16, v190
	v_lshlrev_b32_e32 v190, 16, v165
	v_lshlrev_b32_e32 v191, 16, v166
	v_pk_add_f32 v[22:23], v[22:23], v[190:191]
	v_mul_f32_e32 v190, 0xbfb8aa3b, v164
	v_pk_mul_f32 v[166:167], v[22:23], v[22:23]
	v_exp_f32_e32 v190, v190
	v_add_f32_e32 v165, v166, v167
	v_mov_b32_e32 v166, v129
	v_add_f32_e32 v190, 1.0, v190
	v_add_f32_dpp v165, v165, v165 quad_perm:[1,0,3,2] row_mask:0xf bank_mask:0xf bound_ctrl:1
	s_nop 0
	s_nop 0
	v_add_f32_dpp v165, v165, v165 quad_perm:[2,3,0,1] row_mask:0xf bank_mask:0xf bound_ctrl:1
	s_nop 0
	s_nop 0
	v_add_f32_dpp v165, v165, v165 row_half_mirror row_mask:0xf bank_mask:0xf bound_ctrl:1
	s_nop 0
	s_nop 0
	v_add_f32_dpp v165, v165, v165 row_mirror row_mask:0xf bank_mask:0xf bound_ctrl:1
	s_nop 0
	s_nop 0
	v_mov_b32_dpp v166, v165 row_bcast:15 row_mask:0xa bank_mask:0xf
	v_add_f32_e32 v165, v165, v166
	v_mov_b32_e32 v166, v129
	s_nop 1
	v_mov_b32_dpp v166, v165 row_bcast:31 row_mask:0xc bank_mask:0xf
	v_add_f32_e32 v165, v165, v166
	s_nop 0
	v_readlane_b32 s20, v165, 63
	s_nop 1
	v_fma_f32 v165, s20, v182, v169
	v_cmp_gt_f32_e32 vcc, s33, v165
	v_mul_f32_e32 v166, 0x4b800000, v165
	s_nop 0
	v_cndmask_b32_e32 v165, v165, v166, vcc
	v_rsq_f32_e32 v165, v165
	s_nop 0
	v_mul_f32_e32 v166, 0x45800000, v165
	v_cndmask_b32_e32 v165, v165, v166, vcc
	v_mul_f32_e32 v22, v22, v165
	v_mul_f32_e32 v22, v126, v22
	v_rcp_f32_e32 v191, v190
	s_nop 0
	v_mul_f32_e32 v164, v164, v191
	v_mul_f32_e32 v22, v164, v22
	v_bfe_u32 v164, v22, 16, 1
	v_lshl_add_u64 v[166:167], v[12:13], 0, s[42:43]
	v_add3_u32 v22, v22, v164, s21
	global_store_short_d16_hi v[166:167], v22, off
	v_mul_f32_e32 v22, v23, v165
	v_lshlrev_b32_e32 v23, 16, v163
	v_mul_f32_e32 v163, 0xbfb8aa3b, v23
	v_exp_f32_e32 v163, v163
	v_mul_f32_e32 v22, v127, v22
	v_add_f32_e32 v163, 1.0, v163
	s_nop 0
	v_rcp_f32_e32 v164, v163
	s_nop 0
	v_mul_f32_e32 v23, v23, v164
	v_mul_f32_e32 v22, v23, v22
	v_bfe_u32 v23, v22, 16, 1
	v_add3_u32 v22, v22, v23, s21
	global_store_short_d16_hi v[166:167], v22, off offset:128
	v_lshlrev_b32_e32 v22, 16, v161
	v_lshlrev_b32_e32 v23, 16, v162
	v_lshlrev_b32_e32 v162, 16, v159
	v_lshlrev_b32_e32 v163, 16, v160
	v_pk_add_f32 v[22:23], v[22:23], v[162:163]
	v_mul_f32_e32 v162, 0xbfb8aa3b, v158
	v_pk_mul_f32 v[160:161], v[22:23], v[22:23]
	v_exp_f32_e32 v162, v162
	v_add_f32_e32 v159, v160, v161
	v_mov_b32_e32 v160, v129
	v_add_f32_e32 v162, 1.0, v162
	v_add_f32_dpp v159, v159, v159 quad_perm:[1,0,3,2] row_mask:0xf bank_mask:0xf bound_ctrl:1
	s_nop 1
	v_add_f32_dpp v159, v159, v159 quad_perm:[2,3,0,1] row_mask:0xf bank_mask:0xf bound_ctrl:1
	s_nop 1
	v_add_f32_dpp v159, v159, v159 row_half_mirror row_mask:0xf bank_mask:0xf bound_ctrl:1
	s_nop 1
; __device__ __forceinline__ float bf2f(u16 v) { return __uint_as_float(((unsigned)v) << 16); }
; __device__ __forceinline__ float siluf_(float x) { return x / (1.f + __expf(-x)); }
; __device__ void phase_combine(const P& p, int l, int ntok, float* lds) {
;     ...
; #pragma unroll
;       for (int i = 0; i < 4; ++i) {
;         int row = r0 + i0 + i;
;         float o0 = bf2f((u16)a0[i]) + bf2f((u16)a1[i]), o1 = bf2f((u16)a2[i]) + bf2f((u16)a3[i]);
;         float ss = wave_sum_b(o0 * o0 + o1 * o1);
;         float rstd = rsqrtf(ss * (1.f / 128.f) + 1e-6f);
;         u16* dst = p.nbuf + (size_t)row * D + mixer * 512 + hh * 128 + lane;
;         dst[0] = f2bf(o0 * rstd * ng0 * siluf_(bf2f((u16)g0r[i])));
;         dst[64] = f2bf(o1 * rstd * ng1 * siluf_(bf2f((u16)g1r[i])));
;       }
; #pragma unroll
;       for (int i = 0; i < 4; ++i) {
;         int tr = (tb + i0 + i) & (RL - 1);
;         float up = tr != 0 ? bf2f((u16)ucc[i]) * bf2f((u16)uch[i]) : 0.f;
;         float uc = bf2f((u16)ucc[i + 1]) * bf2f((u16)uch[i + 1]);
;         float un = tr != RL - 1 ? bf2f((u16)ucc[i + 2]) * bf2f((u16)uch[i + 2]) : 0.f;
;         float cv = scw0 * up + scw1 * uc + scw2 * un;
;         p.nbuf[(size_t)(r0 + i0 + i) * D + 1024 + tid] = f2bf(bf2f((u16)cbr[i]) * cv);
;       }
	v_add_f32_dpp v159, v159, v159 row_mirror row_mask:0xf bank_mask:0xf bound_ctrl:1
	s_nop 1
	v_mov_b32_dpp v160, v159 row_bcast:15 row_mask:0xa bank_mask:0xf
	v_add_f32_e32 v159, v159, v160
	v_mov_b32_e32 v160, v129
	s_nop 1
	v_mov_b32_dpp v160, v159 row_bcast:31 row_mask:0xc bank_mask:0xf
	v_add_f32_e32 v159, v159, v160
	s_nop 0
	v_readlane_b32 s20, v159, 63
	s_nop 1
	v_fma_f32 v159, s20, v182, v169
	v_cmp_gt_f32_e32 vcc, s33, v159
	v_mul_f32_e32 v160, 0x4b800000, v159
	s_nop 0
	v_cndmask_b32_e32 v159, v159, v160, vcc
	v_rsq_f32_e32 v159, v159
	s_nop 0
	v_mul_f32_e32 v160, 0x45800000, v159
	v_cndmask_b32_e32 v159, v159, v160, vcc
	v_lshl_add_u64 v[160:161], v[12:13], 0, s[2:3]
	v_mul_f32_e32 v22, v22, v159
	v_mul_f32_e32 v22, v126, v22
	v_rcp_f32_e32 v163, v162
	s_nop 0
	v_mul_f32_e32 v158, v158, v163
	v_mul_f32_e32 v22, v158, v22
	v_bfe_u32 v158, v22, 16, 1
	v_add3_u32 v22, v22, v158, s21
	global_store_short_d16_hi v[160:161], v22, off
	v_mul_f32_e32 v22, v23, v159
	v_lshlrev_b32_e32 v23, 16, v157
	v_mul_f32_e32 v157, 0xbfb8aa3b, v23
	v_exp_f32_e32 v157, v157
	v_mul_f32_e32 v22, v127, v22
	v_add_f32_e32 v157, 1.0, v157
	s_nop 0
	v_rcp_f32_e32 v158, v157
	s_nop 0
	v_mul_f32_e32 v23, v23, v158
	v_mul_f32_e32 v22, v23, v22
	v_bfe_u32 v23, v22, 16, 1
	v_add3_u32 v22, v22, v23, s21
	global_store_short_d16_hi v[160:161], v22, off offset:128
	v_lshlrev_b32_e32 v22, 16, v155
	v_lshlrev_b32_e32 v23, 16, v156
	v_lshlrev_b32_e32 v156, 16, v153
	v_lshlrev_b32_e32 v157, 16, v154
	v_pk_add_f32 v[22:23], v[22:23], v[156:157]
	v_mul_f32_e32 v156, 0xbfb8aa3b, v152
	v_pk_mul_f32 v[154:155], v[22:23], v[22:23]
	v_exp_f32_e32 v156, v156
	v_add_f32_e32 v153, v154, v155
	v_mov_b32_e32 v154, v129
	v_add_f32_e32 v156, 1.0, v156
	v_add_f32_dpp v153, v153, v153 quad_perm:[1,0,3,2] row_mask:0xf bank_mask:0xf bound_ctrl:1
	s_nop 1
	v_add_f32_dpp v153, v153, v153 quad_perm:[2,3,0,1] row_mask:0xf bank_mask:0xf bound_ctrl:1
	s_nop 1
	v_add_f32_dpp v153, v153, v153 row_half_mirror row_mask:0xf bank_mask:0xf bound_ctrl:1
	s_nop 1
	v_add_f32_dpp v153, v153, v153 row_mirror row_mask:0xf bank_mask:0xf bound_ctrl:1
	s_nop 1
	v_mov_b32_dpp v154, v153 row_bcast:15 row_mask:0xa bank_mask:0xf
	v_add_f32_e32 v153, v153, v154
	v_mov_b32_e32 v154, v129
	s_nop 1
	v_mov_b32_dpp v154, v153 row_bcast:31 row_mask:0xc bank_mask:0xf
	v_add_f32_e32 v153, v153, v154
	s_nop 0
	v_readlane_b32 s2, v153, 63
	s_nop 1
	v_fma_f32 v153, s2, v182, v169
	v_cmp_gt_f32_e32 vcc, s33, v153
	v_mul_f32_e32 v154, 0x4b800000, v153
	s_nop 0
	v_cndmask_b32_e32 v153, v153, v154, vcc
	v_rsq_f32_e32 v153, v153
	s_nop 0
	v_mul_f32_e32 v154, 0x45800000, v153
	v_cndmask_b32_e32 v153, v153, v154, vcc
	v_lshl_add_u64 v[154:155], v[12:13], 0, s[0:1]
	v_mul_f32_e32 v22, v22, v153
	v_mul_f32_e32 v22, v126, v22
	v_rcp_f32_e32 v157, v156
	s_nop 0
	v_mul_f32_e32 v152, v152, v157
	v_mul_f32_e32 v22, v152, v22
	v_bfe_u32 v152, v22, 16, 1
	v_add3_u32 v22, v22, v152, s21
	global_store_short_d16_hi v[154:155], v22, off
	v_mul_f32_e32 v22, v23, v153
	v_lshlrev_b32_e32 v23, 16, v149
	v_mul_f32_e32 v149, 0xbfb8aa3b, v23
	v_exp_f32_e32 v149, v149
	v_mul_f32_e32 v22, v127, v22
	v_add_f32_e32 v149, 1.0, v149
	s_and_b32 s0, s46, s58
	s_cmp_lg_u32 s0, 0
	v_rcp_f32_e32 v152, v149
	s_nop 0
	v_mul_f32_e32 v23, v23, v152
	v_mul_f32_e32 v22, v23, v22
	v_bfe_u32 v23, v22, 16, 1
	v_add3_u32 v22, v22, v23, s21
	global_store_short_d16_hi v[154:155], v22, off offset:128
	v_lshlrev_b32_e32 v22, 16, v139
	v_lshlrev_b32_e32 v23, 16, v140
	v_mul_f32_e32 v22, v22, v23
	s_cselect_b64 vcc, -1, 0
	v_cndmask_b32_e32 v22, 0, v22, vcc
	v_lshlrev_b32_e32 v23, 16, v147
	v_lshlrev_b32_e32 v139, 16, v148
	v_mul_f32_e32 v23, v23, v139
	v_lshlrev_b32_e32 v139, 16, v150
	v_lshlrev_b32_e32 v140, 16, v151
	v_mul_f32_e32 v22, v123, v22
	v_mul_f32_e32 v139, v139, v140
	v_fmac_f32_e32 v22, v124, v23
	v_fmac_f32_e32 v22, v125, v139
	v_mul_f32_e32 v22, v22, v138
	v_bfe_u32 v138, v22, 16, 1
	v_add3_u32 v22, v22, v138, s21
	global_store_short_d16_hi v[18:19], v22, off offset:2048
	v_lshlrev_b32_e32 v18, 16, v145
	v_lshlrev_b32_e32 v19, 16, v146
	v_mul_f32_e32 v18, v18, v19
	v_mul_f32_e32 v19, v124, v139
	v_fmac_f32_e32 v19, v123, v23
	v_fmac_f32_e32 v19, v125, v18
	v_lshlrev_b32_e32 v22, 16, v137
	v_mul_f32_e32 v19, v19, v22
	v_bfe_u32 v22, v19, 16, 1
	v_add3_u32 v19, v19, v22, s21
	global_store_short_d16_hi v[20:21], v19, off offset:2048
	v_lshlrev_b32_e32 v19, 16, v143
	v_lshlrev_b32_e32 v20, 16, v144
	v_mul_f32_e32 v19, v19, v20
	v_mul_f32_e32 v20, v124, v18
	v_fmac_f32_e32 v20, v123, v139
	v_fmac_f32_e32 v20, v125, v19
	v_lshlrev_b32_e32 v21, 16, v136
	v_mul_f32_e32 v20, v20, v21
	v_bfe_u32 v21, v20, 16, 1
	v_add3_u32 v20, v20, v21, s21
	s_and_b32 s0, s36, s58
	global_store_short_d16_hi v[2:3], v20, off offset:2048
	v_lshlrev_b32_e32 v2, 16, v141
	v_lshlrev_b32_e32 v3, 16, v142
	s_cmp_lg_u32 s0, s58
	v_mul_f32_e32 v2, v2, v3
	s_cselect_b64 vcc, -1, 0
	v_mul_f32_e32 v3, v124, v19
	v_cndmask_b32_e32 v2, 0, v2, vcc
	v_fmac_f32_e32 v3, v123, v18
	v_fmac_f32_e32 v3, v125, v2
	v_lshlrev_b32_e32 v2, 16, v135
	v_mul_f32_e32 v2, v3, v2
	v_bfe_u32 v3, v2, 16, 1
	s_add_i32 s0, s60, 4
	v_add3_u32 v2, v2, v3, s21
	s_cmp_gt_u32 s60, 11
	s_mov_b32 s60, s0
	global_store_short_d16_hi v[0:1], v2, off offset:2048
	s_cbranch_scc0 .LBB0_94
	v_readlane_b32 s0, v240, 4
	v_readlane_b32 s1, v240, 5
	s_load_dword s0, s[0:1], 0x0
	s_movk_i32 s33, 0x3600
	s_waitcnt lgkmcnt(0)
	s_add_i32 s55, s0, s55
	s_cmp_ge_i32 s55, s72
	s_cbranch_scc0 .LBB0_90
